# phase 3: workgroups 0..63 run their sample-row unit before their tile (on top of the phase-1 reordering)
# baseline (speedup 1.0000x reference)
_Z14fwd_megakernel6Params:
	s_mov_b32 s92, s2
	s_mov_b32 s98, 0
	s_mov_b32 s99, 0
	s_load_dwordx8 s[84:91], s[0:1], 0x80
	s_load_dword s2, s[0:1], 0xa0
	s_load_dwordx16 s[56:71], s[0:1], 0x0
	s_load_dwordx16 s[20:35], s[0:1], 0x40
	v_and_b32_e32 v162, 0x3ff, v0
	v_cmp_eq_u32_e64 s[4:5], 0, v162
	s_waitcnt lgkmcnt(0)
	v_writelane_b32 v251, s2, 0
	s_add_u32 s2, s0, 0x98
	s_addc_u32 s3, s1, 0
	v_writelane_b32 v251, s2, 1
	s_nop 1
	v_writelane_b32 v251, s3, 2
	s_mov_b64 s[2:3], exec
	v_writelane_b32 v251, s4, 3
	s_nop 1
	v_writelane_b32 v251, s5, 4
	s_and_b64 s[4:5], s[2:3], s[4:5]
	s_mov_b64 exec, s[4:5]
	s_cbranch_execz .LBB0_2
	v_mov_b32_e32 v2, 0
	v_mov_b32_e32 v3, v2
	v_mov_b32_e32 v4, v2
	v_mov_b32_e32 v5, v2
	v_mov_b32_e32 v1, 0x20000
	ds_write_b128 v1, v[2:5]

.LBB0_980:
	s_add_u32 s12, s86, 0x400000
	v_lshrrev_b32_e32 v1, 3, v162
	s_addc_u32 s13, s87, 0
	v_lshrrev_b32_e32 v160, 2, v162
	v_and_b32_e32 v163, 0x70, v1
	v_and_b32_e32 v161, 15, v162
	s_andn2_b64 vcc, exec, s[2:3]
	v_bfe_u32 v164, v162, 4, 2
	s_cbranch_vccnz .LBB0_1017
	s_cmp_lg_u32 s98, 0
	s_cbranch_scc1 .Lp3m_go
	s_cmpk_gt_u32 s92, 63
	s_cbranch_scc1 .Lp3m_go
	s_mov_b32 s98, 1
	s_branch .Lp3m_mini
.Lp3m_go:
	v_lshlrev_b32_e32 v3, 4, v162
	v_and_b32_e32 v2, 32, v162
	v_and_b32_e32 v16, 15, v160
	v_bitop3_b32 v14, v3, v2, 48 bitop3:0x6c
	v_and_b32_e32 v15, 64, v162
	v_or_b32_e32 v2, v14, v15
	s_lshl_b32 s1, s0, 1
	v_or_b32_e32 v4, v163, v16
	v_mad_u64_u32 v[130:131], s[4:5], s1, v4, v[2:3]
	v_add_u32_e32 v3, 0x2000, v3
	v_lshrrev_b32_e32 v3, 7, v3
	v_and_b32_e32 v17, 0xf0, v3
	v_or_b32_e32 v3, v17, v16
	v_mad_u64_u32 v[132:133], s[4:5], s1, v3, v[2:3]
	s_ashr_i32 s1, s0, 31
	s_lshl_b64 s[18:19], s[0:1], 9
	s_ashr_i32 s4, s56, 31
	s_mul_i32 s4, s18, s4
	s_mul_hi_u32 s5, s18, s56
	s_ashr_i32 s7, s55, 31
	s_add_i32 s6, s5, s4
	s_lshr_b64 s[4:5], s[0:1], 23
	s_mul_i32 s7, s18, s7
	s_mul_hi_u32 s8, s18, s55
	s_lshr_b32 s3, s23, 6
	s_mul_i32 s5, s4, s56
	s_add_i32 s7, s8, s7
	s_mul_i32 s4, s4, s55
	s_lshr_b32 s2, s23, 8
	s_lshl_b64 s[16:17], s[0:1], 8
	s_lshl_b32 s28, s3, 10
	s_add_i32 s6, s6, s5
	s_add_i32 s7, s7, s4
	s_mul_i32 s4, s18, s55
	s_add_u32 s26, s12, s4
	s_mul_i32 s5, s18, s56
	s_addc_u32 s27, s13, s7
	s_add_i32 s29, s28, 0x10000
	s_add_i32 s30, s28, 0x12000
	s_mov_b32 m0, s29
	s_add_u32 s24, s60, s5
	global_load_lds_dwordx4 v130, s[26:27]
	s_mov_b32 m0, s30
	s_addc_u32 s25, s61, s6
	s_add_i32 s31, s28, 0x2000
	global_load_lds_dwordx4 v132, s[26:27]
	s_mov_b32 m0, s28
	s_add_u32 s4, s26, s16
	global_load_lds_dwordx4 v130, s[24:25]
	s_mov_b32 m0, s31
	s_addc_u32 s5, s27, s17
	s_add_i32 s33, s28, 0x14000
	s_add_i32 s34, s28, 0x16000
	global_load_lds_dwordx4 v132, s[24:25]
	s_mov_b32 m0, s33
	s_add_u32 s6, s24, s16
	global_load_lds_dwordx4 v130, s[4:5]
	s_mov_b32 m0, s34
	s_addc_u32 s7, s25, s17
	s_add_i32 s35, s28, 0x4000
	global_load_lds_dwordx4 v132, s[4:5]
	s_mov_b32 m0, s35
	s_add_i32 s38, s28, 0x6000
	global_load_lds_dwordx4 v130, s[6:7]
	s_mov_b32 m0, s38
	v_mov_b32_e32 v131, 0
	global_load_lds_dwordx4 v132, s[6:7]
	v_mov_b32_e32 v133, v131
	v_lshl_add_u64 v[12:13], s[26:27], 0, v[130:131]
	v_lshl_add_u64 v[10:11], s[26:27], 0, v[132:133]
	v_lshl_add_u64 v[8:9], s[24:25], 0, v[130:131]
	v_lshl_add_u64 v[6:7], s[24:25], 0, v[132:133]
	v_lshl_add_u64 v[4:5], s[4:5], 0, v[130:131]
	s_cmp_lg_u32 s2, 1
	v_lshl_add_u64 v[2:3], s[4:5], 0, v[132:133]
	s_cbranch_scc1 .LBB0_983
	s_barrier

.LBB0_1017:
	s_cmp_eq_u32 s98, 2
	s_cbranch_scc1 .LBB0_1022

.LBB0_1022:
	s_cmp_lg_u32 s98, 1
	s_cbranch_scc1 .Lp3m_cont
	s_mov_b32 s98, 2
	s_waitcnt lgkmcnt(0)
	s_barrier
	s_branch .LBB0_974
